# attention fused softmax+PV: row-sum adds rebalanced into the later MFMA gaps (2 exps only in the first 8 gaps); V group-A LDS reads fill the post-S hazard slots; max-tree nops removed
# speedup vs baseline: 1.0572x; 1.0072x over previous
; __device__ __forceinline__ float half_max(float v) { const unsigned u = __builtin_bit_cast(unsigned, v); auto rr = __builtin_amdgcn_permlane32_swap(u, u, false, false); return fmaxf(__builtin_bit_cast(float, (unsigned)rr[0]), __builtin_bit_cast(float, (unsigned)rr[1])); }
; __device__ __forceinline__ float max3f(float a, float b, float c) { float r; asm("v_max3_f32 %0, %1, %2, %3" : "=v"(r) : "v"(a), "v"(b), "v"(c)); return r; }
; template <bool DIFF> ...
;     ...
;             asm volatile("s_nop 15\n\ts_nop 7" : "+v"(s0), "+v"(s1));
;             float mx;
;             {
;                 float a0 = max3f(s0[0], s0[1], s0[2]), a1 = max3f(s0[3], s0[4], s0[5]), a2 = max3f(s0[6], s0[7], s0[8]), a3 = max3f(s0[9], s0[10], s0[11]);
;                 float b0 = max3f(s1[0], s1[1], s1[2]), b1 = max3f(s1[3], s1[4], s1[5]), b2 = max3f(s1[6], s1[7], s1[8]), b3 = max3f(s1[9], s1[10], s1[11]);
;                 a0 = max3f(a0, s0[12], s0[13]); a1 = max3f(a1, s0[14], s0[15]); b0 = max3f(b0, s1[12], s1[13]); b1 = max3f(b1, s1[14], s1[15]);
;                 a0 = max3f(a0, a1, a2); b0 = max3f(b0, b1, b2); mx = max3f(a0, b0, a3); mx = max3f(mx, b3, b3);
;             }
;             mx = half_max(mx);
;             if (first || __any(mx > 6.0f)) {
.LBB0_1485:
	s_mulk_i32 s77, 0x5000
	v_add_u32_e32 v15, s77, v205
	ds_read_b64_tr_b16 v[212:213], v15 offset:52224
	ds_read_b64_tr_b16 v[214:215], v15 offset:54784
	ds_read_b64_tr_b16 v[216:217], v15 offset:52288
	ds_read_b64_tr_b16 v[218:219], v15 offset:54848
	ds_read_b64_tr_b16 v[220:221], v15 offset:52352
	ds_read_b64_tr_b16 v[222:223], v15 offset:54912
	ds_read_b64_tr_b16 v[224:225], v15 offset:52416
	ds_read_b64_tr_b16 v[226:227], v15 offset:54976
	s_nop 1
	s_xor_b64 s[14:15], s[12:13], -1
	v_max3_f32 v0, v112, v113, v114
	v_max3_f32 v2, v115, v116, v117
	v_max3_f32 v3, v118, v119, v120
	v_max3_f32 v5, v96, v97, v98
	v_max3_f32 v6, v99, v100, v101
	v_max3_f32 v4, v121, v122, v123
	v_max3_f32 v0, v0, v124, v125
	v_max3_f32 v2, v2, v126, v127
	v_max3_f32 v7, v102, v103, v104
	v_max3_f32 v5, v5, v108, v109
	v_max3_f32 v6, v6, v110, v111
	v_max3_f32 v8, v105, v106, v107
	s_and_b64 vcc, exec, s[14:15]
	v_max3_f32 v0, v0, v2, v3
	v_max3_f32 v2, v5, v6, v7
	v_max3_f32 v0, v0, v2, v4
	v_max3_f32 v0, v0, v8, v8
	s_cbranch_vccz .Lattn_full
	s_mov_b32 s14, 0x40c00000
	v_cmp_lt_f32_e32 vcc, s14, v0
	s_cbranch_vccz .LBB0_1492

; template <bool DIFF> ...
;     ...
; #pragma unroll
;             for (int ii = 0; ii < 16; ++ii) { s0[ii] = __builtin_amdgcn_exp2f(s0[ii]); s1[ii] = __builtin_amdgcn_exp2f(s1[ii]); }
;             pk[0][0] = pack8(s0, 0); pk[0][1] = pack8(s0, 8); pk[1][0] = pack8(s1, 0); pk[1][1] = pack8(s1, 8);
;         }
;         if (!late && active) A_PV(t & 3);
.LBB0_1492:
	v_exp_f32_e32 v112, v112
	v_exp_f32_e32 v113, v113
	v_exp_f32_e32 v114, v114
	v_exp_f32_e32 v115, v115
	v_exp_f32_e32 v116, v116
	v_exp_f32_e32 v117, v117
	v_exp_f32_e32 v118, v118
	v_exp_f32_e32 v119, v119
	v_exp_f32_e32 v120, v120
	v_exp_f32_e32 v121, v121
	v_exp_f32_e32 v122, v122
	v_exp_f32_e32 v123, v123
	v_exp_f32_e32 v124, v124
	v_exp_f32_e32 v125, v125
	v_exp_f32_e32 v126, v126
	v_exp_f32_e32 v127, v127
	s_waitcnt lgkmcnt(4)
	ds_read_b64_tr_b16 v[228:229], v15 offset:57344
	ds_read_b64_tr_b16 v[230:231], v15 offset:59904
	ds_read_b64_tr_b16 v[232:233], v15 offset:57408
	ds_read_b64_tr_b16 v[234:235], v15 offset:59968
	ds_read_b64_tr_b16 v[236:237], v15 offset:57472
	ds_read_b64_tr_b16 v[238:239], v15 offset:60032
	ds_read_b64_tr_b16 v[244:245], v15 offset:57536
	ds_read_b64_tr_b16 v[246:247], v15 offset:60096
	v_cvt_pk_bf16_f32 v2, v112, v113
	v_cvt_pk_bf16_f32 v3, v114, v115
	v_cvt_pk_bf16_f32 v4, v116, v117
	v_cvt_pk_bf16_f32 v5, v118, v119
	v_cvt_pk_bf16_f32 v6, v120, v121
	v_cvt_pk_bf16_f32 v7, v122, v123
	v_cvt_pk_bf16_f32 v8, v124, v125
	v_cvt_pk_bf16_f32 v9, v126, v127
	v_add_u32_e32 v14, 0xcc00, v15
	s_waitcnt lgkmcnt(8)
	v_mfma_f32_32x32x16_bf16 v[32:47], v[212:215], v[2:5], v[32:47]
	v_exp_f32_e32 v96, v96
	v_exp_f32_e32 v97, v97
	v_mfma_f32_32x32x16_bf16 v[16:31], v[216:219], v[2:5], v[16:31]
	v_exp_f32_e32 v98, v98
	v_exp_f32_e32 v99, v99
	v_mfma_f32_32x32x16_bf16 v[48:63], v[220:223], v[2:5], v[48:63]
	v_exp_f32_e32 v100, v100
	v_exp_f32_e32 v101, v101
	v_mfma_f32_32x32x16_bf16 v[64:79], v[224:227], v[2:5], v[64:79]
	v_exp_f32_e32 v102, v102
	v_exp_f32_e32 v103, v103
	s_waitcnt lgkmcnt(4)
	ds_read_b64_tr_b16 v[212:213], v15 offset:62464
	ds_read_b64_tr_b16 v[214:215], v15 offset:65024
	ds_read_b64_tr_b16 v[216:217], v15 offset:62528
	ds_read_b64_tr_b16 v[218:219], v15 offset:65088
	ds_read_b64_tr_b16 v[220:221], v15 offset:62592
	ds_read_b64_tr_b16 v[222:223], v15 offset:65152
	ds_read_b64_tr_b16 v[224:225], v15 offset:62656
	ds_read_b64_tr_b16 v[226:227], v15 offset:65216
	s_waitcnt lgkmcnt(8)
	v_mfma_f32_32x32x16_bf16 v[32:47], v[228:231], v[6:9], v[32:47]
	v_exp_f32_e32 v104, v104
	v_exp_f32_e32 v105, v105
	v_mfma_f32_32x32x16_bf16 v[16:31], v[232:235], v[6:9], v[16:31]
	v_exp_f32_e32 v106, v106
	v_exp_f32_e32 v107, v107
	v_mfma_f32_32x32x16_bf16 v[48:63], v[236:239], v[6:9], v[48:63]
	v_exp_f32_e32 v108, v108
	v_exp_f32_e32 v109, v109
	v_mfma_f32_32x32x16_bf16 v[64:79], v[244:247], v[6:9], v[64:79]
	v_exp_f32_e32 v110, v110
	v_exp_f32_e32 v111, v111
	v_cvt_pk_bf16_f32 v10, v96, v97
	v_cvt_pk_bf16_f32 v11, v98, v99
	v_cvt_pk_bf16_f32 v12, v100, v101
	v_cvt_pk_bf16_f32 v13, v102, v103
	s_waitcnt lgkmcnt(4)
	ds_read_b64_tr_b16 v[228:229], v14 offset:15360
	ds_read_b64_tr_b16 v[230:231], v14 offset:17920
	ds_read_b64_tr_b16 v[232:233], v14 offset:15424
	ds_read_b64_tr_b16 v[234:235], v14 offset:17984
	ds_read_b64_tr_b16 v[236:237], v14 offset:15488
	ds_read_b64_tr_b16 v[238:239], v14 offset:18048
	ds_read_b64_tr_b16 v[244:245], v14 offset:15552
	ds_read_b64_tr_b16 v[246:247], v14 offset:18112
	s_waitcnt lgkmcnt(8)
	v_mfma_f32_32x32x16_bf16 v[32:47], v[212:215], v[10:13], v[32:47]
	v_cvt_pk_bf16_f32 v248, v104, v105
	v_cvt_pk_bf16_f32 v249, v106, v107
	v_add_f32_e32 v240, v240, v112
	v_add_f32_e32 v241, v241, v113
	v_add_f32_e32 v242, v242, v114
	v_mfma_f32_32x32x16_bf16 v[16:31], v[216:219], v[10:13], v[16:31]
	v_cvt_pk_bf16_f32 v250, v108, v109
	v_cvt_pk_bf16_f32 v251, v110, v111
	v_add_f32_e32 v243, v243, v115
	v_add_f32_e32 v240, v240, v116
	v_add_f32_e32 v241, v241, v117
	v_mfma_f32_32x32x16_bf16 v[48:63], v[220:223], v[10:13], v[48:63]
	v_add_f32_e32 v242, v242, v118
	v_add_f32_e32 v243, v243, v119
	v_add_f32_e32 v240, v240, v120
	v_add_f32_e32 v241, v241, v121
	v_add_f32_e32 v242, v242, v122
	v_mfma_f32_32x32x16_bf16 v[64:79], v[224:227], v[10:13], v[64:79]
	v_add_f32_e32 v243, v243, v123
	v_add_f32_e32 v240, v240, v124
	v_add_f32_e32 v241, v241, v125
	v_add_f32_e32 v242, v242, v126
	v_add_f32_e32 v243, v243, v127
	s_waitcnt lgkmcnt(0)
	v_mfma_f32_32x32x16_bf16 v[32:47], v[228:231], v[248:251], v[32:47]
	v_add_f32_e32 v240, v240, v96
	v_add_f32_e32 v241, v241, v97
	v_add_f32_e32 v242, v242, v98
	v_add_f32_e32 v243, v243, v99
	v_add_f32_e32 v240, v240, v100
	v_mfma_f32_32x32x16_bf16 v[16:31], v[232:235], v[248:251], v[16:31]
	v_add_f32_e32 v241, v241, v101
	v_add_f32_e32 v242, v242, v102
	v_add_f32_e32 v243, v243, v103
	v_add_f32_e32 v240, v240, v104
	v_add_f32_e32 v241, v241, v105
	v_mfma_f32_32x32x16_bf16 v[48:63], v[236:239], v[248:251], v[48:63]
	v_add_f32_e32 v242, v242, v106
	v_add_f32_e32 v243, v243, v107
	v_add_f32_e32 v240, v240, v108
	v_add_f32_e32 v241, v241, v109
	v_add_f32_e32 v242, v242, v110
	v_mfma_f32_32x32x16_bf16 v[64:79], v[244:247], v[248:251], v[64:79]
	v_add_f32_e32 v243, v243, v111
	s_mov_b64 s[12:13], 0
